# FFN_IN: lower-half SwiGLU epilogue of a tile issued inside the next tile's first k-iteration (memory block + first MFMA block), upper half inside the tile's last k-iteration
# baseline (speedup 1.0000x reference)
.LBB0_678:
	v_lshl_add_u64 v[10:11], s[22:23], 0, v[0:1]
	v_mov_b32_e32 v131, v1
	s_lshl_b32 s7, s7, 5
	v_lshl_add_u64 v[12:13], s[22:23], 0, v[130:131]
	v_mov_b32_e32 v135, v1
	s_and_b32 s7, s7, 0x60
	s_add_i32 m0, s36, 0x18000
	v_lshl_add_u64 v[10:11], v[10:11], 0, s[4:5]
	v_lshl_add_u64 v[14:15], s[20:21], 0, v[134:135]
	v_mov_b32_e32 v133, v1
	s_lshl_b32 s11, s6, 13
	s_lshl_b32 s14, s7, 7
	s_waitcnt vmcnt(2)
	s_barrier
	global_load_lds_dwordx4 v[10:11], off
	v_lshl_add_u64 v[10:11], v[12:13], 0, s[4:5]
	s_add_i32 m0, s36, 0x1a000
	s_add_i32 s40, s36, 0x8000
	s_add_i32 s41, s36, 0xa000
	v_lshl_add_u64 v[16:17], s[20:21], 0, v[132:133]
	global_load_lds_dwordx4 v[10:11], off
	v_lshl_add_u64 v[10:11], v[14:15], 0, s[4:5]
	s_mov_b32 m0, s40
	s_add_u32 s12, s22, 0x40080
	global_load_lds_dwordx4 v[10:11], off
	v_lshl_add_u64 v[10:11], v[16:17], 0, s[4:5]
	s_mov_b32 m0, s41
	s_addc_u32 s13, s23, 0
	global_load_lds_dwordx4 v[10:11], off
	s_add_i32 m0, s36, 0x1c000
	v_lshl_add_u64 v[10:11], s[12:13], 0, v[0:1]
	global_load_lds_dwordx4 v[10:11], off
	v_lshl_add_u64 v[10:11], s[12:13], 0, v[130:131]
	s_add_i32 m0, s36, 0x1e000
	v_and_b32_e32 v9, 15, v2
	global_load_lds_dwordx4 v[10:11], off
	v_lshrrev_b32_e32 v10, 1, v2
	v_and_b32_e32 v10, 24, v10
	v_lshlrev_b32_e32 v11, 1, v10
	v_lshlrev_b32_e32 v2, 2, v2
	v_lshl_or_b32 v142, s6, 6, v9
	v_lshl_or_b32 v9, v9, 6, v11
	v_and_b32_e32 v2, 32, v2
	v_bitop3_b32 v11, v9, s11, v2 bitop3:0xde
	v_bitop3_b32 v143, v9, s14, v2 bitop3:0xde
	v_lshlrev_b32_e32 v2, 14, v7
	v_and_b32_e32 v2, 0xffff8000, v2
	v_lshl_add_u32 v2, v6, 11, v2
	v_and_b32_e32 v6, 1, v7
	v_lshl_or_b32 v2, v6, 6, v2
	v_lshl_add_u32 v136, v8, 1, v2
	v_lshlrev_b32_e32 v2, 14, v3
	v_and_b32_e32 v2, 0xffff8000, v2
	s_waitcnt vmcnt(6)
	v_lshl_add_u32 v2, v4, 11, v2
	v_and_b32_e32 v3, 1, v3
	s_cmpk_lt_u32 s10, 0x100
	v_or_b32_e32 v144, s7, v10
	v_lshl_or_b32 v2, v3, 6, v2
	v_readlane_b32 s6, v252, 28
	s_cselect_b64 s[10:11], -1, 0
	v_mov_b32_e32 v137, v1
	v_lshl_add_u32 v138, v5, 1, v2
	v_mov_b32_e32 v139, v1
	s_mov_b32 s42, 0
	v_add_u32_e32 v145, 0, v11
	v_readlane_b32 s34, v252, 27
	s_mov_b32 s35, s6
	s_barrier
	v_readlane_b32 s7, v252, 29
	s_mov_b64 s[100:101], 0
	s_branch .LBB0_681

.LBB0_681:
	s_add_i32 s42, s42, 1
	v_readlane_b32 s6, v252, 7
	s_mul_i32 s6, s42, s6
	s_mul_hi_u32 s7, s42, s46
	s_add_i32 s7, s7, s6
	s_mul_i32 s6, s42, s46
	s_add_u32 s16, s6, s2
	s_addc_u32 s17, s7, s33
	v_mov_b64_e32 v[248:249], 0xb00
	v_cmp_gt_i64_e32 vcc, s[16:17], v[162:163]
	v_cmp_lt_i64_e64 s[6:7], s[16:17], v[248:249]
	s_cbranch_vccnz .LBB0_683
	s_ashr_i32 s12, s16, 31
	s_lshr_b32 s12, s12, 29
	s_add_i32 s12, s16, s12
	s_ashr_i32 s13, s12, 3
	s_and_b32 s12, s12, -8
	s_sub_i32 s12, s16, s12
	s_cmp_lt_i32 s12, 0
	s_movk_i32 s14, 0x161
	s_cselect_b32 s14, s14, 0x160
	s_mul_i32 s12, s14, s12
	s_add_i32 s12, s12, s13
	s_mul_hi_i32 s13, s12, 0x2e8ba2e9
	s_lshr_b32 s14, s13, 31
	s_ashr_i32 s13, s13, 5
	s_add_i32 s13, s13, s14
	s_lshl_b32 s14, s13, 3
	s_sub_i32 s15, 0x80, s14
	s_min_i32 s15, s15, 8
	s_abs_i32 s16, s15
	v_cvt_f32_u32_e32 v248, s16
	s_sub_i32 s18, 0, s16
	s_mulk_i32 s13, 0xb0
	s_sub_i32 s13, s12, s13
	v_rcp_iflag_f32_e32 v248, v248
	s_abs_i32 s12, s13
	s_xor_b32 s17, s13, s15
	s_ashr_i32 s17, s17, 31
	v_mul_f32_e32 v248, 0x4f7ffffe, v248
	v_cvt_u32_f32_e32 v248, v248
	s_nop 0
	v_readfirstlane_b32 s19, v248
	s_mul_i32 s18, s18, s19
	s_mul_hi_u32 s18, s19, s18
	s_add_i32 s19, s19, s18
	s_mul_hi_u32 s18, s12, s19
	s_mul_i32 s19, s18, s16
	s_sub_i32 s12, s12, s19
	s_add_i32 s24, s18, 1
	s_sub_i32 s19, s12, s16
	s_cmp_ge_u32 s12, s16
	s_cselect_b32 s18, s24, s18
	s_cselect_b32 s12, s19, s12
	s_add_i32 s19, s18, 1
	s_cmp_ge_u32 s12, s16
	s_cselect_b32 s12, s19, s18
	s_xor_b32 s12, s12, s17
	s_sub_i32 s12, s12, s17
	s_mul_i32 s15, s12, s15
	s_sub_i32 s13, s13, s15
	s_add_i32 s14, s13, s14
.LBB0_683:
	s_ashr_i32 s15, s14, 31
	s_lshl_b64 s[16:17], s[14:15], 19
	v_readlane_b32 s18, v254, 8
	v_readlane_b32 s19, v254, 9
	s_add_u32 s16, s18, s16
	s_addc_u32 s17, s19, s17
	s_and_b64 s[18:19], s[6:7], exec
	s_cselect_b32 s15, s17, s21
	s_cselect_b32 s43, s16, s20
	s_ashr_i32 s13, s12, 31
	s_lshl_b64 s[18:19], s[12:13], 19
	s_add_u32 s18, s0, s18
	s_addc_u32 s19, s28, s19
	s_and_b64 s[24:25], s[6:7], exec
	s_cselect_b32 s13, s19, s23
	s_cselect_b32 s47, s18, s22
	s_add_u32 s20, s20, 0x40080
	s_addc_u32 s21, s21, 0
	s_add_u32 s48, s22, 0x100
	s_addc_u32 s49, s23, 0
	s_mov_b32 s50, -2
	s_add_u32 s22, s20, 0xfffc0080
	s_addc_u32 s23, s21, -1
	s_add_i32 s51, 0, 0x10000
	s_cmp_eq_u32 s50, 12
	s_cselect_b32 s25, s15, s23
	s_cselect_b32 s24, s43, s22
	v_add_u32_e32 v140, s51, v143
	s_cselect_b32 s23, s13, s49
	s_cselect_b32 s22, s47, s48
	s_add_i32 s54, 0, 0x14000
	ds_read_b128 v[146:149], v140
	ds_read_b128 v[150:153], v140 offset:1024
	ds_read_b128 v[154:157], v140 offset:2048
	ds_read_b128 v[158:161], v140 offset:3072
	v_add_u32_e32 v140, s54, v143
	ds_read_b128 v[166:169], v140
	ds_read_b128 v[170:173], v140 offset:1024
	ds_read_b128 v[174:177], v140 offset:2048
	ds_read_b128 v[178:181], v140 offset:3072
	v_lshl_add_u64 v[140:141], s[20:21], 0, v[136:137]
	s_add_i32 m0, s36, 0xc000
	ds_read_b128 v[182:185], v145
	ds_read_b128 v[186:189], v145 offset:1024
	ds_read_b128 v[190:193], v145 offset:2048
	ds_read_b128 v[194:197], v145 offset:3072
	ds_read_b128 v[198:201], v145 offset:4096
	ds_read_b128 v[210:213], v145 offset:5120
	ds_read_b128 v[214:217], v145 offset:6144
	ds_read_b128 v[218:221], v145 offset:7168
	global_load_lds_dwordx4 v[140:141], off
	v_lshl_add_u64 v[140:141], s[20:21], 0, v[138:139]
	s_add_i32 m0, s36, 0xe000
	s_nop 0
	global_load_lds_dwordx4 v[140:141], off
	s_cmp_eq_u64 s[100:101], 0
	s_cbranch_scc1 .Lsw_f1
	v_pk_mul_f32 v[226:227], v[62:63], v[244:245]
	v_pk_mul_f32 v[228:229], v[64:65], v[244:245]
	v_pk_mul_f32 v[230:231], v[54:55], v[244:245]
	v_pk_mul_f32 v[232:233], v[56:57], v[244:245]
	v_exp_f32_e32 v226, v226
	v_exp_f32_e32 v227, v227
	v_exp_f32_e32 v228, v228
	v_exp_f32_e32 v229, v229
	v_exp_f32_e32 v230, v230
	v_exp_f32_e32 v231, v231
	v_exp_f32_e32 v232, v232
	v_exp_f32_e32 v233, v233
	v_pk_add_f32 v[226:227], v[226:227], 1.0 op_sel_hi:[1,0]
	v_pk_add_f32 v[228:229], v[228:229], 1.0 op_sel_hi:[1,0]
	v_pk_add_f32 v[230:231], v[230:231], 1.0 op_sel_hi:[1,0]
	v_pk_add_f32 v[232:233], v[232:233], 1.0 op_sel_hi:[1,0]
	v_rcp_f32_e32 v226, v226
	v_rcp_f32_e32 v227, v227
	v_rcp_f32_e32 v228, v228
	v_rcp_f32_e32 v229, v229
	v_rcp_f32_e32 v230, v230
	v_rcp_f32_e32 v231, v231
	v_rcp_f32_e32 v232, v232
	v_rcp_f32_e32 v233, v233
	v_pk_mul_f32 v[62:63], v[62:63], v[226:227]
	v_pk_mul_f32 v[64:65], v[64:65], v[228:229]
	v_pk_mul_f32 v[54:55], v[54:55], v[230:231]
	v_pk_mul_f32 v[56:57], v[56:57], v[232:233]
	v_pk_mul_f32 v[62:63], v[62:63], v[58:59]
	v_pk_mul_f32 v[64:65], v[64:65], v[60:61]
	v_pk_mul_f32 v[54:55], v[54:55], v[50:51]
	v_pk_mul_f32 v[56:57], v[56:57], v[52:53]
	v_cvt_pk_bf16_f32 v234, v62, v63
	v_cvt_pk_bf16_f32 v235, v64, v65
	v_cvt_pk_bf16_f32 v236, v54, v55
	v_cvt_pk_bf16_f32 v237, v56, v57
	v_add_u32_e32 v242, 0xb0000, v246
	global_store_dwordx4 v242, v[234:237], s[100:101]
	v_pk_mul_f32 v[226:227], v[46:47], v[244:245]
	v_pk_mul_f32 v[228:229], v[48:49], v[244:245]
	v_pk_mul_f32 v[230:231], v[38:39], v[244:245]
	v_pk_mul_f32 v[232:233], v[40:41], v[244:245]
	v_exp_f32_e32 v226, v226
	v_exp_f32_e32 v227, v227
	v_exp_f32_e32 v228, v228
	v_exp_f32_e32 v229, v229
	v_exp_f32_e32 v230, v230
	v_exp_f32_e32 v231, v231
	v_exp_f32_e32 v232, v232
	v_exp_f32_e32 v233, v233
	v_pk_add_f32 v[226:227], v[226:227], 1.0 op_sel_hi:[1,0]
	v_pk_add_f32 v[228:229], v[228:229], 1.0 op_sel_hi:[1,0]
	v_pk_add_f32 v[230:231], v[230:231], 1.0 op_sel_hi:[1,0]
	v_pk_add_f32 v[232:233], v[232:233], 1.0 op_sel_hi:[1,0]
	v_rcp_f32_e32 v226, v226
	v_rcp_f32_e32 v227, v227
	v_rcp_f32_e32 v228, v228
	v_rcp_f32_e32 v229, v229
	v_rcp_f32_e32 v230, v230
	v_rcp_f32_e32 v231, v231
	v_rcp_f32_e32 v232, v232
	v_rcp_f32_e32 v233, v233
	v_pk_mul_f32 v[46:47], v[46:47], v[226:227]
	v_pk_mul_f32 v[48:49], v[48:49], v[228:229]
	v_pk_mul_f32 v[38:39], v[38:39], v[230:231]
	v_pk_mul_f32 v[40:41], v[40:41], v[232:233]
	v_pk_mul_f32 v[46:47], v[46:47], v[42:43]
	v_pk_mul_f32 v[48:49], v[48:49], v[44:45]
	v_pk_mul_f32 v[38:39], v[38:39], v[34:35]
	v_pk_mul_f32 v[40:41], v[40:41], v[36:37]
	v_cvt_pk_bf16_f32 v238, v46, v47
	v_cvt_pk_bf16_f32 v239, v48, v49
	v_cvt_pk_bf16_f32 v240, v38, v39
	v_cvt_pk_bf16_f32 v241, v40, v41
	v_add_u32_e32 v243, 0xc6000, v246
	global_store_dwordx4 v243, v[238:241], s[100:101]
.Lsw_f1:
	s_waitcnt vmcnt(8)
	s_waitcnt lgkmcnt(0)
	s_barrier
	s_cmp_eq_u64 s[100:101], 0
	s_cbranch_scc1 .Lsw_f2a
	s_setprio 1
	s_waitcnt lgkmcnt(0)
	v_mfma_f32_16x16x32_bf16 v[126:129], v[146:149], v[182:185], 0
	v_pk_mul_f32 v[226:227], v[30:31], v[244:245]
	v_pk_mul_f32 v[228:229], v[32:33], v[244:245]
	v_mfma_f32_16x16x32_bf16 v[118:121], v[154:157], v[182:185], 0
	v_pk_mul_f32 v[230:231], v[22:23], v[244:245]
	v_pk_mul_f32 v[232:233], v[24:25], v[244:245]
	v_mfma_f32_16x16x32_bf16 v[110:113], v[146:149], v[190:193], 0
	v_exp_f32_e32 v226, v226
	v_exp_f32_e32 v227, v227
	v_exp_f32_e32 v228, v228
	v_mfma_f32_16x16x32_bf16 v[102:105], v[154:157], v[190:193], 0
	v_exp_f32_e32 v229, v229
	v_exp_f32_e32 v230, v230
	v_mfma_f32_16x16x32_bf16 v[94:97], v[146:149], v[198:201], 0
	v_exp_f32_e32 v231, v231
	v_exp_f32_e32 v232, v232
	v_mfma_f32_16x16x32_bf16 v[86:89], v[154:157], v[198:201], 0
	v_exp_f32_e32 v233, v233
	v_pk_add_f32 v[226:227], v[226:227], 1.0 op_sel_hi:[1,0]
	v_pk_add_f32 v[228:229], v[228:229], 1.0 op_sel_hi:[1,0]
	v_mfma_f32_16x16x32_bf16 v[78:81], v[146:149], v[214:217], 0
	v_pk_add_f32 v[230:231], v[230:231], 1.0 op_sel_hi:[1,0]
	v_pk_add_f32 v[232:233], v[232:233], 1.0 op_sel_hi:[1,0]
	v_mfma_f32_16x16x32_bf16 v[70:73], v[154:157], v[214:217], 0
	v_rcp_f32_e32 v226, v226
	v_rcp_f32_e32 v227, v227
	v_rcp_f32_e32 v228, v228
	v_mfma_f32_16x16x32_bf16 v[126:129], v[150:153], v[186:189], v[126:129]
	v_rcp_f32_e32 v229, v229
	v_rcp_f32_e32 v230, v230
	v_mfma_f32_16x16x32_bf16 v[118:121], v[158:161], v[186:189], v[118:121]
	v_rcp_f32_e32 v231, v231
	v_rcp_f32_e32 v232, v232
	v_mfma_f32_16x16x32_bf16 v[110:113], v[150:153], v[194:197], v[110:113]
	v_rcp_f32_e32 v233, v233
	v_pk_mul_f32 v[30:31], v[30:31], v[226:227]
	v_pk_mul_f32 v[32:33], v[32:33], v[228:229]
	v_mfma_f32_16x16x32_bf16 v[102:105], v[158:161], v[194:197], v[102:105]
	v_pk_mul_f32 v[22:23], v[22:23], v[230:231]
	v_pk_mul_f32 v[24:25], v[24:25], v[232:233]
	v_mfma_f32_16x16x32_bf16 v[94:97], v[150:153], v[210:213], v[94:97]
	v_pk_mul_f32 v[30:31], v[30:31], v[26:27]
	v_pk_mul_f32 v[32:33], v[32:33], v[28:29]
	v_mfma_f32_16x16x32_bf16 v[86:89], v[158:161], v[210:213], v[86:89]
	v_pk_mul_f32 v[22:23], v[22:23], v[18:19]
	v_pk_mul_f32 v[24:25], v[24:25], v[20:21]
	v_cvt_pk_bf16_f32 v234, v30, v31
	v_mfma_f32_16x16x32_bf16 v[78:81], v[150:153], v[218:221], v[78:81]
	v_cvt_pk_bf16_f32 v235, v32, v33
	v_cvt_pk_bf16_f32 v236, v22, v23
	v_mfma_f32_16x16x32_bf16 v[70:73], v[158:161], v[218:221], v[70:73]
	v_cvt_pk_bf16_f32 v237, v24, v25
	v_add_u32_e32 v242, 0xdc000, v246
	global_store_dwordx4 v242, v[234:237], s[100:101]
	s_setprio 0
	s_setprio 1
	v_mfma_f32_16x16x32_bf16 v[122:125], v[166:169], v[182:185], 0
	v_pk_mul_f32 v[226:227], v[14:15], v[244:245]
	v_pk_mul_f32 v[228:229], v[16:17], v[244:245]
	v_mfma_f32_16x16x32_bf16 v[114:117], v[174:177], v[182:185], 0
	v_pk_mul_f32 v[230:231], v[6:7], v[244:245]
	v_pk_mul_f32 v[232:233], v[8:9], v[244:245]
	v_mfma_f32_16x16x32_bf16 v[106:109], v[166:169], v[190:193], 0
	v_exp_f32_e32 v226, v226
	v_exp_f32_e32 v227, v227
	v_exp_f32_e32 v228, v228
	v_mfma_f32_16x16x32_bf16 v[98:101], v[174:177], v[190:193], 0
	v_exp_f32_e32 v229, v229
	v_exp_f32_e32 v230, v230
	v_mfma_f32_16x16x32_bf16 v[90:93], v[166:169], v[198:201], 0
	v_exp_f32_e32 v231, v231
	v_exp_f32_e32 v232, v232
	v_mfma_f32_16x16x32_bf16 v[82:85], v[174:177], v[198:201], 0
	v_exp_f32_e32 v233, v233
	v_pk_add_f32 v[226:227], v[226:227], 1.0 op_sel_hi:[1,0]
	v_pk_add_f32 v[228:229], v[228:229], 1.0 op_sel_hi:[1,0]
	v_mfma_f32_16x16x32_bf16 v[74:77], v[166:169], v[214:217], 0
	v_pk_add_f32 v[230:231], v[230:231], 1.0 op_sel_hi:[1,0]
	v_pk_add_f32 v[232:233], v[232:233], 1.0 op_sel_hi:[1,0]
	v_mfma_f32_16x16x32_bf16 v[66:69], v[174:177], v[214:217], 0
	v_rcp_f32_e32 v226, v226
	v_rcp_f32_e32 v227, v227
	v_rcp_f32_e32 v228, v228
	v_mfma_f32_16x16x32_bf16 v[122:125], v[170:173], v[186:189], v[122:125]
	v_rcp_f32_e32 v229, v229
	v_rcp_f32_e32 v230, v230
	v_mfma_f32_16x16x32_bf16 v[114:117], v[178:181], v[186:189], v[114:117]
	v_rcp_f32_e32 v231, v231
	v_rcp_f32_e32 v232, v232
	v_mfma_f32_16x16x32_bf16 v[106:109], v[170:173], v[194:197], v[106:109]
	v_rcp_f32_e32 v233, v233
	v_pk_mul_f32 v[14:15], v[14:15], v[226:227]
	v_pk_mul_f32 v[16:17], v[16:17], v[228:229]
	v_mfma_f32_16x16x32_bf16 v[98:101], v[178:181], v[194:197], v[98:101]
	v_pk_mul_f32 v[6:7], v[6:7], v[230:231]
	v_pk_mul_f32 v[8:9], v[8:9], v[232:233]
	v_mfma_f32_16x16x32_bf16 v[90:93], v[170:173], v[210:213], v[90:93]
	v_pk_mul_f32 v[14:15], v[14:15], v[10:11]
	v_pk_mul_f32 v[16:17], v[16:17], v[12:13]
	v_mfma_f32_16x16x32_bf16 v[82:85], v[178:181], v[210:213], v[82:85]
	v_pk_mul_f32 v[6:7], v[6:7], v[2:3]
	v_pk_mul_f32 v[8:9], v[8:9], v[4:5]
	v_cvt_pk_bf16_f32 v238, v14, v15
	v_mfma_f32_16x16x32_bf16 v[74:77], v[170:173], v[218:221], v[74:77]
	v_cvt_pk_bf16_f32 v239, v16, v17
	v_cvt_pk_bf16_f32 v240, v6, v7
	v_mfma_f32_16x16x32_bf16 v[66:69], v[178:181], v[218:221], v[66:69]
	v_cvt_pk_bf16_f32 v241, v8, v9
	v_add_u32_e32 v243, 0xf2000, v246
	global_store_dwordx4 v243, v[238:241], s[100:101]
	s_setprio 0
	s_branch .Lsw_f2b
.Lsw_f2a:
	s_setprio 1
	s_waitcnt lgkmcnt(0)
	v_mfma_f32_16x16x32_bf16 v[126:129], v[146:149], v[182:185], 0
	v_mfma_f32_16x16x32_bf16 v[118:121], v[154:157], v[182:185], 0
	v_mfma_f32_16x16x32_bf16 v[110:113], v[146:149], v[190:193], 0
	v_mfma_f32_16x16x32_bf16 v[102:105], v[154:157], v[190:193], 0
	v_mfma_f32_16x16x32_bf16 v[94:97], v[146:149], v[198:201], 0
	v_mfma_f32_16x16x32_bf16 v[86:89], v[154:157], v[198:201], 0
	v_mfma_f32_16x16x32_bf16 v[78:81], v[146:149], v[214:217], 0
	v_mfma_f32_16x16x32_bf16 v[70:73], v[154:157], v[214:217], 0
	v_mfma_f32_16x16x32_bf16 v[126:129], v[150:153], v[186:189], v[126:129]
	v_mfma_f32_16x16x32_bf16 v[118:121], v[158:161], v[186:189], v[118:121]
	v_mfma_f32_16x16x32_bf16 v[110:113], v[150:153], v[194:197], v[110:113]
	v_mfma_f32_16x16x32_bf16 v[102:105], v[158:161], v[194:197], v[102:105]
	v_mfma_f32_16x16x32_bf16 v[94:97], v[150:153], v[210:213], v[94:97]
	v_mfma_f32_16x16x32_bf16 v[86:89], v[158:161], v[210:213], v[86:89]
	v_mfma_f32_16x16x32_bf16 v[78:81], v[150:153], v[218:221], v[78:81]
	v_mfma_f32_16x16x32_bf16 v[70:73], v[158:161], v[218:221], v[70:73]
	s_setprio 0
	s_setprio 1
	v_mfma_f32_16x16x32_bf16 v[122:125], v[166:169], v[182:185], 0
	v_mfma_f32_16x16x32_bf16 v[114:117], v[174:177], v[182:185], 0
	v_mfma_f32_16x16x32_bf16 v[106:109], v[166:169], v[190:193], 0
	v_mfma_f32_16x16x32_bf16 v[98:101], v[174:177], v[190:193], 0
	v_mfma_f32_16x16x32_bf16 v[90:93], v[166:169], v[198:201], 0
	v_mfma_f32_16x16x32_bf16 v[82:85], v[174:177], v[198:201], 0
	v_mfma_f32_16x16x32_bf16 v[74:77], v[166:169], v[214:217], 0
	v_mfma_f32_16x16x32_bf16 v[66:69], v[174:177], v[214:217], 0
	v_mfma_f32_16x16x32_bf16 v[122:125], v[170:173], v[186:189], v[122:125]
	v_mfma_f32_16x16x32_bf16 v[114:117], v[178:181], v[186:189], v[114:117]
	v_mfma_f32_16x16x32_bf16 v[106:109], v[170:173], v[194:197], v[106:109]
	v_mfma_f32_16x16x32_bf16 v[98:101], v[178:181], v[194:197], v[98:101]
	v_mfma_f32_16x16x32_bf16 v[90:93], v[170:173], v[210:213], v[90:93]
	v_mfma_f32_16x16x32_bf16 v[82:85], v[178:181], v[210:213], v[82:85]
	v_mfma_f32_16x16x32_bf16 v[74:77], v[170:173], v[218:221], v[74:77]
	v_mfma_f32_16x16x32_bf16 v[66:69], v[178:181], v[218:221], v[66:69]
	s_setprio 0
.Lsw_f2b:
	s_barrier
	s_add_i32 s51, s51, s29
	v_lshl_add_u64 v[140:141], s[22:23], 0, v[0:1]
	s_mov_b32 m0, s51
	ds_read_b128 v[182:185], v145 offset:16384
	ds_read_b128 v[186:189], v145 offset:17408
	ds_read_b128 v[190:193], v145 offset:18432
	ds_read_b128 v[194:197], v145 offset:19456
	ds_read_b128 v[198:201], v145 offset:20480
	ds_read_b128 v[210:213], v145 offset:21504
	ds_read_b128 v[214:217], v145 offset:22528
	ds_read_b128 v[218:221], v145 offset:23552
	global_load_lds_dwordx4 v[140:141], off
	s_add_i32 m0, s51, 0x2000
	s_add_u32 s52, s22, 0x40000
	v_lshl_add_u64 v[202:203], s[22:23], 0, v[130:131]
	s_addc_u32 s53, s23, 0
	s_add_i32 s51, s54, s29
	global_load_lds_dwordx4 v[202:203], off
	v_lshl_add_u64 v[206:207], s[52:53], 0, v[0:1]
	s_mov_b32 m0, s51
	v_lshl_add_u64 v[222:223], s[24:25], 0, v[132:133]
	global_load_lds_dwordx4 v[206:207], off
	v_lshl_add_u64 v[206:207], s[52:53], 0, v[130:131]
	s_add_i32 m0, s51, 0x2000
	s_nop 0
	global_load_lds_dwordx4 v[206:207], off
	v_lshl_add_u64 v[206:207], s[24:25], 0, v[134:135]
	s_mov_b32 m0, s36
	s_nop 0
	global_load_lds_dwordx4 v[206:207], off
	s_mov_b32 m0, s37
	s_nop 0
	global_load_lds_dwordx4 v[222:223], off
	s_waitcnt vmcnt(8)
	s_waitcnt lgkmcnt(0)
	s_barrier
	s_setprio 1
	s_waitcnt lgkmcnt(0)
	v_mfma_f32_16x16x32_bf16 v[62:65], v[146:149], v[182:185], 0
	v_mfma_f32_16x16x32_bf16 v[54:57], v[154:157], v[182:185], 0
	v_mfma_f32_16x16x32_bf16 v[46:49], v[146:149], v[190:193], 0
	v_mfma_f32_16x16x32_bf16 v[38:41], v[154:157], v[190:193], 0
	v_mfma_f32_16x16x32_bf16 v[30:33], v[146:149], v[198:201], 0
	v_mfma_f32_16x16x32_bf16 v[22:25], v[154:157], v[198:201], 0
	v_mfma_f32_16x16x32_bf16 v[14:17], v[146:149], v[214:217], 0
	v_mfma_f32_16x16x32_bf16 v[6:9], v[154:157], v[214:217], 0
	v_mfma_f32_16x16x32_bf16 v[62:65], v[150:153], v[186:189], v[62:65]
	v_mfma_f32_16x16x32_bf16 v[54:57], v[158:161], v[186:189], v[54:57]
	v_mfma_f32_16x16x32_bf16 v[46:49], v[150:153], v[194:197], v[46:49]
	v_mfma_f32_16x16x32_bf16 v[38:41], v[158:161], v[194:197], v[38:41]
	v_mfma_f32_16x16x32_bf16 v[30:33], v[150:153], v[210:213], v[30:33]
	v_mfma_f32_16x16x32_bf16 v[22:25], v[158:161], v[210:213], v[22:25]
	v_mfma_f32_16x16x32_bf16 v[14:17], v[150:153], v[218:221], v[14:17]
	v_mfma_f32_16x16x32_bf16 v[6:9], v[158:161], v[218:221], v[6:9]
	s_setprio 0
	s_setprio 1
	v_mfma_f32_16x16x32_bf16 v[58:61], v[166:169], v[182:185], 0
	v_mfma_f32_16x16x32_bf16 v[50:53], v[174:177], v[182:185], 0
	v_mfma_f32_16x16x32_bf16 v[42:45], v[166:169], v[190:193], 0
	v_mfma_f32_16x16x32_bf16 v[34:37], v[174:177], v[190:193], 0
	v_mfma_f32_16x16x32_bf16 v[26:29], v[166:169], v[198:201], 0
	v_mfma_f32_16x16x32_bf16 v[18:21], v[174:177], v[198:201], 0
	v_mfma_f32_16x16x32_bf16 v[10:13], v[166:169], v[214:217], 0
	v_mfma_f32_16x16x32_bf16 v[2:5], v[174:177], v[214:217], 0
	v_mfma_f32_16x16x32_bf16 v[58:61], v[170:173], v[186:189], v[58:61]
	v_mfma_f32_16x16x32_bf16 v[50:53], v[178:181], v[186:189], v[50:53]
	v_mfma_f32_16x16x32_bf16 v[42:45], v[170:173], v[194:197], v[42:45]
	v_mfma_f32_16x16x32_bf16 v[34:37], v[178:181], v[194:197], v[34:37]
	v_mfma_f32_16x16x32_bf16 v[26:29], v[170:173], v[210:213], v[26:29]
	v_mfma_f32_16x16x32_bf16 v[18:21], v[178:181], v[210:213], v[18:21]
	v_mfma_f32_16x16x32_bf16 v[10:13], v[170:173], v[218:221], v[10:13]
	v_mfma_f32_16x16x32_bf16 v[2:5], v[178:181], v[218:221], v[2:5]
	s_setprio 0
	s_barrier
	s_add_i32 s51, 0, 0x18000
	s_add_i32 s52, 0, 0x1c000
	v_add_u32_e32 v158, s51, v143
	v_add_u32_e32 v178, s52, v143
	ds_read_b128 v[146:149], v158
	ds_read_b128 v[150:153], v158 offset:1024
	ds_read_b128 v[154:157], v158 offset:2048
	ds_read_b128 v[158:161], v158 offset:3072
	ds_read_b128 v[166:169], v178
	ds_read_b128 v[170:173], v178 offset:1024
	ds_read_b128 v[174:177], v178 offset:2048
	ds_read_b128 v[178:181], v178 offset:3072
	s_add_u32 s24, s24, 0x40000
	s_addc_u32 s25, s25, 0
	s_mov_b32 m0, s38
	v_lshl_add_u64 v[224:225], s[24:25], 0, v[134:135]
	ds_read_b128 v[182:185], v145 offset:32768
	ds_read_b128 v[186:189], v145 offset:33792
	ds_read_b128 v[190:193], v145 offset:34816
	ds_read_b128 v[194:197], v145 offset:35840
	ds_read_b128 v[198:201], v145 offset:36864
	ds_read_b128 v[210:213], v145 offset:37888
	ds_read_b128 v[214:217], v145 offset:38912
	ds_read_b128 v[218:221], v145 offset:39936
	global_load_lds_dwordx4 v[224:225], off
	v_lshl_add_u64 v[224:225], s[24:25], 0, v[132:133]
	s_mov_b32 m0, s39
	s_nop 0
	global_load_lds_dwordx4 v[224:225], off
	s_waitcnt vmcnt(8)
	s_waitcnt lgkmcnt(0)
	s_barrier
	s_setprio 1
	s_waitcnt lgkmcnt(0)
	v_mfma_f32_16x16x32_bf16 v[126:129], v[146:149], v[182:185], v[126:129]
	v_mfma_f32_16x16x32_bf16 v[118:121], v[154:157], v[182:185], v[118:121]
	v_mfma_f32_16x16x32_bf16 v[110:113], v[146:149], v[190:193], v[110:113]
	v_mfma_f32_16x16x32_bf16 v[102:105], v[154:157], v[190:193], v[102:105]
	v_mfma_f32_16x16x32_bf16 v[94:97], v[146:149], v[198:201], v[94:97]
	v_mfma_f32_16x16x32_bf16 v[86:89], v[154:157], v[198:201], v[86:89]
	v_mfma_f32_16x16x32_bf16 v[78:81], v[146:149], v[214:217], v[78:81]
	v_mfma_f32_16x16x32_bf16 v[70:73], v[154:157], v[214:217], v[70:73]
	v_mfma_f32_16x16x32_bf16 v[126:129], v[150:153], v[186:189], v[126:129]
	v_mfma_f32_16x16x32_bf16 v[118:121], v[158:161], v[186:189], v[118:121]
	v_mfma_f32_16x16x32_bf16 v[110:113], v[150:153], v[194:197], v[110:113]
	v_mfma_f32_16x16x32_bf16 v[102:105], v[158:161], v[194:197], v[102:105]
	v_mfma_f32_16x16x32_bf16 v[94:97], v[150:153], v[210:213], v[94:97]
	v_mfma_f32_16x16x32_bf16 v[86:89], v[158:161], v[210:213], v[86:89]
	v_mfma_f32_16x16x32_bf16 v[78:81], v[150:153], v[218:221], v[78:81]
	v_mfma_f32_16x16x32_bf16 v[70:73], v[158:161], v[218:221], v[70:73]
	s_setprio 0
	s_setprio 1
	v_mfma_f32_16x16x32_bf16 v[122:125], v[166:169], v[182:185], v[122:125]
	v_mfma_f32_16x16x32_bf16 v[114:117], v[174:177], v[182:185], v[114:117]
	v_mfma_f32_16x16x32_bf16 v[106:109], v[166:169], v[190:193], v[106:109]
	v_mfma_f32_16x16x32_bf16 v[98:101], v[174:177], v[190:193], v[98:101]
	v_mfma_f32_16x16x32_bf16 v[90:93], v[166:169], v[198:201], v[90:93]
	v_mfma_f32_16x16x32_bf16 v[82:85], v[174:177], v[198:201], v[82:85]
	v_mfma_f32_16x16x32_bf16 v[74:77], v[166:169], v[214:217], v[74:77]
	v_mfma_f32_16x16x32_bf16 v[66:69], v[174:177], v[214:217], v[66:69]
	v_mfma_f32_16x16x32_bf16 v[122:125], v[170:173], v[186:189], v[122:125]
	v_mfma_f32_16x16x32_bf16 v[114:117], v[178:181], v[186:189], v[114:117]
	v_mfma_f32_16x16x32_bf16 v[106:109], v[170:173], v[194:197], v[106:109]
	v_mfma_f32_16x16x32_bf16 v[98:101], v[178:181], v[194:197], v[98:101]
	v_mfma_f32_16x16x32_bf16 v[90:93], v[170:173], v[210:213], v[90:93]
	v_mfma_f32_16x16x32_bf16 v[82:85], v[178:181], v[210:213], v[82:85]
	v_mfma_f32_16x16x32_bf16 v[74:77], v[170:173], v[218:221], v[74:77]
	v_mfma_f32_16x16x32_bf16 v[66:69], v[178:181], v[218:221], v[66:69]
	s_setprio 0
	s_barrier
	s_add_i32 s24, s51, s29
	v_lshl_add_u64 v[140:141], v[140:141], 0, s[4:5]
	s_mov_b32 m0, s24
	ds_read_b128 v[182:185], v145 offset:49152
	ds_read_b128 v[186:189], v145 offset:50176
	ds_read_b128 v[190:193], v145 offset:51200
	ds_read_b128 v[194:197], v145 offset:52224
	ds_read_b128 v[198:201], v145 offset:53248
	ds_read_b128 v[210:213], v145 offset:54272
	ds_read_b128 v[214:217], v145 offset:55296
	ds_read_b128 v[218:221], v145 offset:56320
	global_load_lds_dwordx4 v[140:141], off
	s_add_i32 m0, s24, 0x2000
	s_add_u32 s22, s22, 0x40080
	v_lshl_add_u64 v[140:141], v[202:203], 0, s[4:5]
	s_addc_u32 s23, s23, 0
	s_add_i32 s24, s52, s29
	global_load_lds_dwordx4 v[140:141], off
	v_lshl_add_u64 v[140:141], s[22:23], 0, v[0:1]
	s_mov_b32 m0, s24
	s_nop 0
	global_load_lds_dwordx4 v[140:141], off
	v_lshl_add_u64 v[140:141], s[22:23], 0, v[130:131]
	s_add_i32 m0, s24, 0x2000
	s_nop 0
	global_load_lds_dwordx4 v[140:141], off
	v_lshl_add_u64 v[140:141], v[206:207], 0, s[4:5]
	s_mov_b32 m0, s40
	s_nop 0
	global_load_lds_dwordx4 v[140:141], off
	v_lshl_add_u64 v[140:141], v[222:223], 0, s[4:5]
	s_mov_b32 m0, s41
	s_nop 0
	global_load_lds_dwordx4 v[140:141], off
	s_waitcnt vmcnt(8)
	s_waitcnt lgkmcnt(0)
	s_barrier
	s_setprio 1
	s_waitcnt lgkmcnt(0)
	v_mfma_f32_16x16x32_bf16 v[62:65], v[146:149], v[182:185], v[62:65]
	v_mfma_f32_16x16x32_bf16 v[54:57], v[154:157], v[182:185], v[54:57]
	v_mfma_f32_16x16x32_bf16 v[46:49], v[146:149], v[190:193], v[46:49]
	v_mfma_f32_16x16x32_bf16 v[38:41], v[154:157], v[190:193], v[38:41]
	v_mfma_f32_16x16x32_bf16 v[30:33], v[146:149], v[198:201], v[30:33]
	v_mfma_f32_16x16x32_bf16 v[22:25], v[154:157], v[198:201], v[22:25]
	v_mfma_f32_16x16x32_bf16 v[14:17], v[146:149], v[214:217], v[14:17]
	v_mfma_f32_16x16x32_bf16 v[6:9], v[154:157], v[214:217], v[6:9]
	v_mfma_f32_16x16x32_bf16 v[62:65], v[150:153], v[186:189], v[62:65]
	v_mfma_f32_16x16x32_bf16 v[54:57], v[158:161], v[186:189], v[54:57]
	v_mfma_f32_16x16x32_bf16 v[46:49], v[150:153], v[194:197], v[46:49]
	v_mfma_f32_16x16x32_bf16 v[38:41], v[158:161], v[194:197], v[38:41]
	v_mfma_f32_16x16x32_bf16 v[30:33], v[150:153], v[210:213], v[30:33]
	v_mfma_f32_16x16x32_bf16 v[22:25], v[158:161], v[210:213], v[22:25]
	v_mfma_f32_16x16x32_bf16 v[14:17], v[150:153], v[218:221], v[14:17]
	v_mfma_f32_16x16x32_bf16 v[6:9], v[158:161], v[218:221], v[6:9]
	s_setprio 0
	s_setprio 1
	v_mfma_f32_16x16x32_bf16 v[58:61], v[166:169], v[182:185], v[58:61]
	v_mfma_f32_16x16x32_bf16 v[50:53], v[174:177], v[182:185], v[50:53]
	v_mfma_f32_16x16x32_bf16 v[42:45], v[166:169], v[190:193], v[42:45]
	v_mfma_f32_16x16x32_bf16 v[34:37], v[174:177], v[190:193], v[34:37]
	v_mfma_f32_16x16x32_bf16 v[26:29], v[166:169], v[198:201], v[26:29]
	v_mfma_f32_16x16x32_bf16 v[18:21], v[174:177], v[198:201], v[18:21]
	v_mfma_f32_16x16x32_bf16 v[10:13], v[166:169], v[214:217], v[10:13]
	v_mfma_f32_16x16x32_bf16 v[2:5], v[174:177], v[214:217], v[2:5]
	v_mfma_f32_16x16x32_bf16 v[58:61], v[170:173], v[186:189], v[58:61]
	v_mfma_f32_16x16x32_bf16 v[50:53], v[178:181], v[186:189], v[50:53]
	v_mfma_f32_16x16x32_bf16 v[42:45], v[170:173], v[194:197], v[42:45]
	v_mfma_f32_16x16x32_bf16 v[34:37], v[178:181], v[194:197], v[34:37]
	v_mfma_f32_16x16x32_bf16 v[26:29], v[170:173], v[210:213], v[26:29]
	v_mfma_f32_16x16x32_bf16 v[18:21], v[178:181], v[210:213], v[18:21]
	v_mfma_f32_16x16x32_bf16 v[10:13], v[170:173], v[218:221], v[10:13]
	v_mfma_f32_16x16x32_bf16 v[2:5], v[178:181], v[218:221], v[2:5]
	s_setprio 0
	s_barrier
	s_add_i32 s50, s50, 2
	s_add_u32 s20, s20, 0x100
	s_addc_u32 s21, s21, 0
	s_add_u32 s48, s48, 0x100
	s_addc_u32 s49, s49, 0

.LBB0_687:
	s_andn2_b64 vcc, exec, s[6:7]
	s_mov_b64 s[20:21], -1
	s_cbranch_vccnz .LBB0_680
	s_andn2_b64 vcc, exec, s[8:9]
	s_cbranch_vccnz .LBB0_679
	s_barrier
	s_branch .LBB0_679
.LBB0_690:
	v_pk_mul_f32 v[226:227], v[62:63], v[244:245]
	v_pk_mul_f32 v[228:229], v[64:65], v[244:245]
	v_pk_mul_f32 v[230:231], v[54:55], v[244:245]
	v_pk_mul_f32 v[232:233], v[56:57], v[244:245]
	v_exp_f32_e32 v226, v226
	v_exp_f32_e32 v227, v227
	v_exp_f32_e32 v228, v228
	v_exp_f32_e32 v229, v229
	v_exp_f32_e32 v230, v230
	v_exp_f32_e32 v231, v231
	v_exp_f32_e32 v232, v232
	v_exp_f32_e32 v233, v233
	v_pk_add_f32 v[226:227], v[226:227], 1.0 op_sel_hi:[1,0]
	v_pk_add_f32 v[228:229], v[228:229], 1.0 op_sel_hi:[1,0]
	v_pk_add_f32 v[230:231], v[230:231], 1.0 op_sel_hi:[1,0]
	v_pk_add_f32 v[232:233], v[232:233], 1.0 op_sel_hi:[1,0]
	v_rcp_f32_e32 v226, v226
	v_rcp_f32_e32 v227, v227
	v_rcp_f32_e32 v228, v228
	v_rcp_f32_e32 v229, v229
	v_rcp_f32_e32 v230, v230
	v_rcp_f32_e32 v231, v231
	v_rcp_f32_e32 v232, v232
	v_rcp_f32_e32 v233, v233
	v_pk_mul_f32 v[62:63], v[62:63], v[226:227]
	v_pk_mul_f32 v[64:65], v[64:65], v[228:229]
	v_pk_mul_f32 v[54:55], v[54:55], v[230:231]
	v_pk_mul_f32 v[56:57], v[56:57], v[232:233]
	v_pk_mul_f32 v[62:63], v[62:63], v[58:59]
	v_pk_mul_f32 v[64:65], v[64:65], v[60:61]
	v_pk_mul_f32 v[54:55], v[54:55], v[50:51]
	v_pk_mul_f32 v[56:57], v[56:57], v[52:53]
	v_cvt_pk_bf16_f32 v234, v62, v63
	v_cvt_pk_bf16_f32 v235, v64, v65
	v_cvt_pk_bf16_f32 v236, v54, v55
	v_cvt_pk_bf16_f32 v237, v56, v57
	v_add_u32_e32 v242, 0xb0000, v246
	global_store_dwordx4 v242, v[234:237], s[100:101]
	v_pk_mul_f32 v[226:227], v[46:47], v[244:245]
	v_pk_mul_f32 v[228:229], v[48:49], v[244:245]
	v_pk_mul_f32 v[230:231], v[38:39], v[244:245]
	v_pk_mul_f32 v[232:233], v[40:41], v[244:245]
	v_exp_f32_e32 v226, v226
	v_exp_f32_e32 v227, v227
	v_exp_f32_e32 v228, v228
	v_exp_f32_e32 v229, v229
	v_exp_f32_e32 v230, v230
	v_exp_f32_e32 v231, v231
	v_exp_f32_e32 v232, v232
	v_exp_f32_e32 v233, v233
	v_pk_add_f32 v[226:227], v[226:227], 1.0 op_sel_hi:[1,0]
	v_pk_add_f32 v[228:229], v[228:229], 1.0 op_sel_hi:[1,0]
	v_pk_add_f32 v[230:231], v[230:231], 1.0 op_sel_hi:[1,0]
	v_pk_add_f32 v[232:233], v[232:233], 1.0 op_sel_hi:[1,0]
	v_rcp_f32_e32 v226, v226
	v_rcp_f32_e32 v227, v227
	v_rcp_f32_e32 v228, v228
	v_rcp_f32_e32 v229, v229
	v_rcp_f32_e32 v230, v230
	v_rcp_f32_e32 v231, v231
	v_rcp_f32_e32 v232, v232
	v_rcp_f32_e32 v233, v233
	v_pk_mul_f32 v[46:47], v[46:47], v[226:227]
	v_pk_mul_f32 v[48:49], v[48:49], v[228:229]
	v_pk_mul_f32 v[38:39], v[38:39], v[230:231]
	v_pk_mul_f32 v[40:41], v[40:41], v[232:233]
	v_pk_mul_f32 v[46:47], v[46:47], v[42:43]
	v_pk_mul_f32 v[48:49], v[48:49], v[44:45]
	v_pk_mul_f32 v[38:39], v[38:39], v[34:35]
	v_pk_mul_f32 v[40:41], v[40:41], v[36:37]
	v_cvt_pk_bf16_f32 v238, v46, v47
	v_cvt_pk_bf16_f32 v239, v48, v49
	v_cvt_pk_bf16_f32 v240, v38, v39
	v_cvt_pk_bf16_f32 v241, v40, v41
	v_add_u32_e32 v243, 0xc6000, v246
	global_store_dwordx4 v243, v[238:241], s[100:101]
	v_pk_mul_f32 v[226:227], v[30:31], v[244:245]
	v_pk_mul_f32 v[228:229], v[32:33], v[244:245]
	v_pk_mul_f32 v[230:231], v[22:23], v[244:245]
	v_pk_mul_f32 v[232:233], v[24:25], v[244:245]
	v_exp_f32_e32 v226, v226
	v_exp_f32_e32 v227, v227
	v_exp_f32_e32 v228, v228
	v_exp_f32_e32 v229, v229
	v_exp_f32_e32 v230, v230
	v_exp_f32_e32 v231, v231
	v_exp_f32_e32 v232, v232
	v_exp_f32_e32 v233, v233
	v_pk_add_f32 v[226:227], v[226:227], 1.0 op_sel_hi:[1,0]
	v_pk_add_f32 v[228:229], v[228:229], 1.0 op_sel_hi:[1,0]
	v_pk_add_f32 v[230:231], v[230:231], 1.0 op_sel_hi:[1,0]
	v_pk_add_f32 v[232:233], v[232:233], 1.0 op_sel_hi:[1,0]
	v_rcp_f32_e32 v226, v226
	v_rcp_f32_e32 v227, v227
	v_rcp_f32_e32 v228, v228
	v_rcp_f32_e32 v229, v229
	v_rcp_f32_e32 v230, v230
	v_rcp_f32_e32 v231, v231
	v_rcp_f32_e32 v232, v232
	v_rcp_f32_e32 v233, v233
	v_pk_mul_f32 v[30:31], v[30:31], v[226:227]
	v_pk_mul_f32 v[32:33], v[32:33], v[228:229]
	v_pk_mul_f32 v[22:23], v[22:23], v[230:231]
	v_pk_mul_f32 v[24:25], v[24:25], v[232:233]
	v_pk_mul_f32 v[30:31], v[30:31], v[26:27]
	v_pk_mul_f32 v[32:33], v[32:33], v[28:29]
	v_pk_mul_f32 v[22:23], v[22:23], v[18:19]
	v_pk_mul_f32 v[24:25], v[24:25], v[20:21]
	v_cvt_pk_bf16_f32 v234, v30, v31
	v_cvt_pk_bf16_f32 v235, v32, v33
	v_cvt_pk_bf16_f32 v236, v22, v23
	v_cvt_pk_bf16_f32 v237, v24, v25
	v_add_u32_e32 v242, 0xdc000, v246
	global_store_dwordx4 v242, v[234:237], s[100:101]
	v_pk_mul_f32 v[226:227], v[14:15], v[244:245]
	v_pk_mul_f32 v[228:229], v[16:17], v[244:245]
	v_pk_mul_f32 v[230:231], v[6:7], v[244:245]
	v_pk_mul_f32 v[232:233], v[8:9], v[244:245]
	v_exp_f32_e32 v226, v226
	v_exp_f32_e32 v227, v227
	v_exp_f32_e32 v228, v228
	v_exp_f32_e32 v229, v229
	v_exp_f32_e32 v230, v230
	v_exp_f32_e32 v231, v231
	v_exp_f32_e32 v232, v232
	v_exp_f32_e32 v233, v233
	v_pk_add_f32 v[226:227], v[226:227], 1.0 op_sel_hi:[1,0]
	v_pk_add_f32 v[228:229], v[228:229], 1.0 op_sel_hi:[1,0]
	v_pk_add_f32 v[230:231], v[230:231], 1.0 op_sel_hi:[1,0]
	v_pk_add_f32 v[232:233], v[232:233], 1.0 op_sel_hi:[1,0]
	v_rcp_f32_e32 v226, v226
	v_rcp_f32_e32 v227, v227
	v_rcp_f32_e32 v228, v228
	v_rcp_f32_e32 v229, v229
	v_rcp_f32_e32 v230, v230
	v_rcp_f32_e32 v231, v231
	v_rcp_f32_e32 v232, v232
	v_rcp_f32_e32 v233, v233
	v_pk_mul_f32 v[14:15], v[14:15], v[226:227]
	v_pk_mul_f32 v[16:17], v[16:17], v[228:229]
	v_pk_mul_f32 v[6:7], v[6:7], v[230:231]
	v_pk_mul_f32 v[8:9], v[8:9], v[232:233]
	v_pk_mul_f32 v[14:15], v[14:15], v[10:11]
	v_pk_mul_f32 v[16:17], v[16:17], v[12:13]
	v_pk_mul_f32 v[6:7], v[6:7], v[2:3]
	v_pk_mul_f32 v[8:9], v[8:9], v[4:5]
	v_cvt_pk_bf16_f32 v238, v14, v15
	v_cvt_pk_bf16_f32 v239, v16, v17
	v_cvt_pk_bf16_f32 v240, v6, v7
	v_cvt_pk_bf16_f32 v241, v8, v9
	v_add_u32_e32 v243, 0xf2000, v246
	global_store_dwordx4 v243, v[238:241], s[100:101]
	s_waitcnt vmcnt(0)
	s_barrier
